# GEMM K-loop LDS-DMA sources as SGPR base + 32-bit lane offset (no per-lane 64-bit VALU adds), on top of lean no-gate epilogue
# speedup vs baseline: 1.0107x; 1.0107x over previous
; #define PG8_STAGE(bufoff, gbase, voff) do { _Pragma("unroll") for (int _i = 0; _i < 2; ++_i) \
;         __builtin_amdgcn_global_load_lds((const unsigned*)((const char*)(gbase) + (voff)[_i]), (PG8_LAS unsigned*)(lds + (bufoff) + ldsw + _i * 8192), 16, 0, 0); } while (0)
; #define PG8_LDA(dst, b, h) do { _Pragma("unroll") for (int m = 0; m < 4; ++m) _Pragma("unroll") for (int k = 0; k < 2; ++k) dst[m][k] = *(const PG8_LAS bf16x8*)(lds + PG8_SA(b, h) + aoff + m * 2048 + k * 1024); } while (0)
; #define PG8_LDB(dst, b, h) do { _Pragma("unroll") for (int n = 0; n < 2; ++n) _Pragma("unroll") for (int k = 0; k < 2; ++k) dst[n][k] = *(const PG8_LAS bf16x8*)(lds + PG8_SB(b, h) + boff + n * 2048 + k * 1024); } while (0)
; #define PG8_MMA(ai, bj, At, Bt) do { __builtin_amdgcn_s_setprio(1); _Pragma("unroll") for (int m = 0; m < 4; ++m) _Pragma("unroll") for (int n = 0; n < 2; ++n) _Pragma("unroll") for (int k = 0; k < 2; ++k) \
;         acc[ai][bj][m][n] = __builtin_amdgcn_mfma_f32_16x16x32_bf16(Bt[n][k], At[m][k], acc[ai][bj][m][n], 0, 0, 0); __builtin_amdgcn_s_setprio(0); } while (0)
; #define PG8_WAIT_V(n) asm volatile("s_waitcnt vmcnt(" #n ")" ::: "memory")
; #define PG8_WAIT_L(n) asm volatile("s_waitcnt lgkmcnt(" #n ")" ::: "memory")
; #define PG8_BAR __builtin_amdgcn_s_barrier()
; #define PG8_SCHED __builtin_amdgcn_sched_barrier(0)
; template <class Epi, class Sched, bool ALIGN_EPI = false, bool SP2 = false>
; __device__ __forceinline__ void gemm_phase(PG8_LAS unsigned char* lds, const Gemm g, const Sched& S, const Epi& E) {
;     ...
;             PG8_LDB(B0, 0, 0); PG8_LDB(B1, 0, 1); PG8_SCHED; PG8_LDA(At, 0, 0); PG8_STAGE(PG8_SA(1, 1), a1 + hstep, voffA);
;             PG8_WAIT_V(8); PG8_WAIT_L(0); PG8_BAR; PG8_MMA(0, 0, At, B0); PG8_MMA(0, 1, At, B1); PG8_BAR; PG8_SCHED;
;             PG8_LDA(At, 0, 1); PG8_STAGE(PG8_SB(0, 0), b2, voffB); PG8_STAGE(PG8_SB(0, 1), b2 + hstep, voffB); PG8_STAGE(PG8_SA(0, 0), a2, voffA);
;             PG8_WAIT_V(8); PG8_WAIT_L(0); PG8_BAR; PG8_MMA(1, 0, At, B0); PG8_MMA(1, 1, At, B1); PG8_BAR; PG8_SCHED;
.LBB0_410:
	s_add_i32 vcc_hi, s28, 2
	s_add_u32 s86, s14, 0x80
	s_addc_u32 s29, s15, 0
	s_add_i32 s88, 0, 0x10000
	s_cmp_eq_u32 s83, s28
	s_cselect_b32 s29, s30, s29
	s_cselect_b32 s28, s31, s86
	s_cselect_b32 s87, s37, vcc_lo
	s_cselect_b32 s86, s45, s47
	s_add_i32 s89, 0, 0x14000
	v_add_u32_e32 v86, s88, v161
	v_add_u32_e32 v172, s89, v161
	ds_read_b128 v[74:77], v86
	ds_read_b128 v[78:81], v86 offset:1024
	ds_read_b128 v[82:85], v86 offset:2048
	ds_read_b128 v[86:89], v86 offset:3072
	ds_read_b128 v[156:159], v172
	ds_read_b128 v[164:167], v172 offset:1024
	ds_read_b128 v[168:171], v172 offset:2048
	ds_read_b128 v[172:175], v172 offset:3072
	s_add_i32 m0, s61, 0xc000
	ds_read_b128 v[176:179], v163
	ds_read_b128 v[180:183], v163 offset:1024
	ds_read_b128 v[184:187], v163 offset:2048
	ds_read_b128 v[188:191], v163 offset:3072
	ds_read_b128 v[192:195], v163 offset:4096
	ds_read_b128 v[196:199], v163 offset:5120
	ds_read_b128 v[200:203], v163 offset:6144
	ds_read_b128 v[210:213], v163 offset:7168
	global_load_lds_dwordx4 v152, s[14:15]
	s_add_i32 m0, s61, 0xe000
	s_nop 0
	global_load_lds_dwordx4 v154, s[14:15]
	s_waitcnt vmcnt(8)
	s_waitcnt lgkmcnt(0)
	s_barrier
	s_setprio 1
	s_waitcnt lgkmcnt(0)
	v_mfma_f32_16x16x32_bf16 v[142:145], v[74:77], v[176:179], v[142:145]
	v_mfma_f32_16x16x32_bf16 v[138:141], v[82:85], v[176:179], v[138:141]
	v_mfma_f32_16x16x32_bf16 v[126:129], v[74:77], v[184:187], v[126:129]
	v_mfma_f32_16x16x32_bf16 v[122:125], v[82:85], v[184:187], v[122:125]
	v_mfma_f32_16x16x32_bf16 v[110:113], v[74:77], v[192:195], v[110:113]
	v_mfma_f32_16x16x32_bf16 v[106:109], v[82:85], v[192:195], v[106:109]
	v_mfma_f32_16x16x32_bf16 v[94:97], v[74:77], v[200:203], v[94:97]
	v_mfma_f32_16x16x32_bf16 v[90:93], v[82:85], v[200:203], v[90:93]
	v_mfma_f32_16x16x32_bf16 v[142:145], v[78:81], v[180:183], v[142:145]
	v_mfma_f32_16x16x32_bf16 v[138:141], v[86:89], v[180:183], v[138:141]
	v_mfma_f32_16x16x32_bf16 v[126:129], v[78:81], v[188:191], v[126:129]
	v_mfma_f32_16x16x32_bf16 v[122:125], v[86:89], v[188:191], v[122:125]
	v_mfma_f32_16x16x32_bf16 v[110:113], v[78:81], v[196:199], v[110:113]
	v_mfma_f32_16x16x32_bf16 v[106:109], v[86:89], v[196:199], v[106:109]
	v_mfma_f32_16x16x32_bf16 v[94:97], v[78:81], v[210:213], v[94:97]
	v_mfma_f32_16x16x32_bf16 v[90:93], v[86:89], v[210:213], v[90:93]
	s_setprio 0
	s_setprio 1
	v_mfma_f32_16x16x32_bf16 v[134:137], v[156:159], v[176:179], v[134:137]
	v_mfma_f32_16x16x32_bf16 v[130:133], v[168:171], v[176:179], v[130:133]
	v_mfma_f32_16x16x32_bf16 v[118:121], v[156:159], v[184:187], v[118:121]
	v_mfma_f32_16x16x32_bf16 v[114:117], v[168:171], v[184:187], v[114:117]
	v_mfma_f32_16x16x32_bf16 v[102:105], v[156:159], v[192:195], v[102:105]
	v_mfma_f32_16x16x32_bf16 v[98:101], v[168:171], v[192:195], v[98:101]
	v_mfma_f32_16x16x32_bf16 v[70:73], v[156:159], v[200:203], v[70:73]
	v_mfma_f32_16x16x32_bf16 v[66:69], v[168:171], v[200:203], v[66:69]
	v_mfma_f32_16x16x32_bf16 v[134:137], v[164:167], v[180:183], v[134:137]
	v_mfma_f32_16x16x32_bf16 v[130:133], v[172:175], v[180:183], v[130:133]
	v_mfma_f32_16x16x32_bf16 v[118:121], v[164:167], v[188:191], v[118:121]
	v_mfma_f32_16x16x32_bf16 v[114:117], v[172:175], v[188:191], v[114:117]
	v_mfma_f32_16x16x32_bf16 v[102:105], v[164:167], v[196:199], v[102:105]
	v_mfma_f32_16x16x32_bf16 v[98:101], v[172:175], v[196:199], v[98:101]
	v_mfma_f32_16x16x32_bf16 v[70:73], v[164:167], v[210:213], v[70:73]
	v_mfma_f32_16x16x32_bf16 v[66:69], v[172:175], v[210:213], v[66:69]
	s_setprio 0
	s_barrier
	s_add_i32 s88, s88, s62
	s_mov_b64 s[100:101], s[86:87]
	s_mov_b32 m0, s88
	ds_read_b128 v[176:179], v163 offset:16384
	ds_read_b128 v[180:183], v163 offset:17408
	ds_read_b128 v[184:187], v163 offset:18432
	ds_read_b128 v[188:191], v163 offset:19456
	ds_read_b128 v[192:195], v163 offset:20480
	ds_read_b128 v[196:199], v163 offset:21504
	ds_read_b128 v[200:203], v163 offset:22528
	ds_read_b128 v[210:213], v163 offset:23552
	global_load_lds_dwordx4 v0, s[86:87]
	s_add_i32 m0, s88, 0x2000
	s_add_i32 s88, s89, s62
	global_load_lds_dwordx4 v150, s[86:87]
	s_mov_b32 m0, s88
	s_add_u32 s86, s86, s10
	s_addc_u32 s87, s87, 0
	global_load_lds_dwordx4 v0, s[86:87]
	s_add_i32 m0, s88, 0x2000
	s_nop 0
	global_load_lds_dwordx4 v150, s[86:87]
	s_mov_b32 m0, s61
	s_nop 0
	global_load_lds_dwordx4 v146, s[28:29]
	s_mov_b32 m0, s77
	s_nop 0
	global_load_lds_dwordx4 v148, s[28:29]
	s_waitcnt vmcnt(8)
	s_waitcnt lgkmcnt(0)
	s_barrier
	s_setprio 1
	s_waitcnt lgkmcnt(0)
	v_mfma_f32_16x16x32_bf16 v[62:65], v[74:77], v[176:179], v[62:65]
	v_mfma_f32_16x16x32_bf16 v[58:61], v[82:85], v[176:179], v[58:61]
	v_mfma_f32_16x16x32_bf16 v[46:49], v[74:77], v[184:187], v[46:49]
	v_mfma_f32_16x16x32_bf16 v[42:45], v[82:85], v[184:187], v[42:45]
	v_mfma_f32_16x16x32_bf16 v[30:33], v[74:77], v[192:195], v[30:33]
	v_mfma_f32_16x16x32_bf16 v[26:29], v[82:85], v[192:195], v[26:29]
	v_mfma_f32_16x16x32_bf16 v[14:17], v[74:77], v[200:203], v[14:17]
	v_mfma_f32_16x16x32_bf16 v[10:13], v[82:85], v[200:203], v[10:13]
	v_mfma_f32_16x16x32_bf16 v[62:65], v[78:81], v[180:183], v[62:65]
	v_mfma_f32_16x16x32_bf16 v[58:61], v[86:89], v[180:183], v[58:61]
	v_mfma_f32_16x16x32_bf16 v[46:49], v[78:81], v[188:191], v[46:49]
	v_mfma_f32_16x16x32_bf16 v[42:45], v[86:89], v[188:191], v[42:45]
	v_mfma_f32_16x16x32_bf16 v[30:33], v[78:81], v[196:199], v[30:33]
	v_mfma_f32_16x16x32_bf16 v[26:29], v[86:89], v[196:199], v[26:29]
	v_mfma_f32_16x16x32_bf16 v[14:17], v[78:81], v[210:213], v[14:17]
	v_mfma_f32_16x16x32_bf16 v[10:13], v[86:89], v[210:213], v[10:13]
	s_setprio 0
	s_setprio 1
	v_mfma_f32_16x16x32_bf16 v[54:57], v[156:159], v[176:179], v[54:57]
	v_mfma_f32_16x16x32_bf16 v[50:53], v[168:171], v[176:179], v[50:53]
	v_mfma_f32_16x16x32_bf16 v[38:41], v[156:159], v[184:187], v[38:41]
	v_mfma_f32_16x16x32_bf16 v[34:37], v[168:171], v[184:187], v[34:37]
	v_mfma_f32_16x16x32_bf16 v[22:25], v[156:159], v[192:195], v[22:25]
	v_mfma_f32_16x16x32_bf16 v[18:21], v[168:171], v[192:195], v[18:21]
	v_mfma_f32_16x16x32_bf16 v[6:9], v[156:159], v[200:203], v[6:9]
	v_mfma_f32_16x16x32_bf16 v[2:5], v[168:171], v[200:203], v[2:5]
	v_mfma_f32_16x16x32_bf16 v[54:57], v[164:167], v[180:183], v[54:57]
	v_mfma_f32_16x16x32_bf16 v[50:53], v[172:175], v[180:183], v[50:53]
	v_mfma_f32_16x16x32_bf16 v[38:41], v[164:167], v[188:191], v[38:41]
	v_mfma_f32_16x16x32_bf16 v[34:37], v[172:175], v[188:191], v[34:37]
	v_mfma_f32_16x16x32_bf16 v[22:25], v[164:167], v[196:199], v[22:25]
	v_mfma_f32_16x16x32_bf16 v[18:21], v[172:175], v[196:199], v[18:21]
	v_mfma_f32_16x16x32_bf16 v[6:9], v[164:167], v[210:213], v[6:9]
	v_mfma_f32_16x16x32_bf16 v[2:5], v[172:175], v[210:213], v[2:5]
	s_setprio 0
	s_barrier
; #define PG8_STAGE(bufoff, gbase, voff) do { _Pragma("unroll") for (int _i = 0; _i < 2; ++_i) \
;         __builtin_amdgcn_global_load_lds((const unsigned*)((const char*)(gbase) + (voff)[_i]), (PG8_LAS unsigned*)(lds + (bufoff) + ldsw + _i * 8192), 16, 0, 0); } while (0)
; #define PG8_LDA(dst, b, h) do { _Pragma("unroll") for (int m = 0; m < 4; ++m) _Pragma("unroll") for (int k = 0; k < 2; ++k) dst[m][k] = *(const PG8_LAS bf16x8*)(lds + PG8_SA(b, h) + aoff + m * 2048 + k * 1024); } while (0)
; #define PG8_LDB(dst, b, h) do { _Pragma("unroll") for (int n = 0; n < 2; ++n) _Pragma("unroll") for (int k = 0; k < 2; ++k) dst[n][k] = *(const PG8_LAS bf16x8*)(lds + PG8_SB(b, h) + boff + n * 2048 + k * 1024); } while (0)
; #define PG8_MMA(ai, bj, At, Bt) do { __builtin_amdgcn_s_setprio(1); _Pragma("unroll") for (int m = 0; m < 4; ++m) _Pragma("unroll") for (int n = 0; n < 2; ++n) _Pragma("unroll") for (int k = 0; k < 2; ++k) \
;         acc[ai][bj][m][n] = __builtin_amdgcn_mfma_f32_16x16x32_bf16(Bt[n][k], At[m][k], acc[ai][bj][m][n], 0, 0, 0); __builtin_amdgcn_s_setprio(0); } while (0)
; #define PG8_WAIT_V(n) asm volatile("s_waitcnt vmcnt(" #n ")" ::: "memory")
; #define PG8_WAIT_L(n) asm volatile("s_waitcnt lgkmcnt(" #n ")" ::: "memory")
; #define PG8_BAR __builtin_amdgcn_s_barrier()
; #define PG8_SCHED __builtin_amdgcn_sched_barrier(0)
; template <class Epi, class Sched, bool ALIGN_EPI = false, bool SP2 = false>
; __device__ __forceinline__ void gemm_phase(PG8_LAS unsigned char* lds, const Gemm g, const Sched& S, const Epi& E) {
;     ...
;             PG8_LDB(B0, 1, 0); PG8_LDB(B1, 1, 1); PG8_SCHED; PG8_LDA(At, 1, 0); PG8_STAGE(PG8_SA(0, 1), a2 + hstep, voffA);
;             PG8_WAIT_V(8); PG8_WAIT_L(0); PG8_BAR; PG8_MMA(0, 0, At, B0); PG8_MMA(0, 1, At, B1); PG8_BAR; PG8_SCHED;
;             PG8_LDA(At, 1, 1); PG8_STAGE(PG8_SB(1, 0), b3, voffB); PG8_STAGE(PG8_SB(1, 1), b3 + hstep, voffB); PG8_STAGE(PG8_SA(1, 0), a3, voffA);
;             PG8_WAIT_V(8); PG8_WAIT_L(0); PG8_BAR; PG8_MMA(1, 0, At, B0); PG8_MMA(1, 1, At, B1); PG8_BAR; PG8_SCHED;
	v_add_u32_e32 v86, 0x18000, v161
	v_add_u32_e32 v172, 0x1c000, v161
	ds_read_b128 v[74:77], v86
	ds_read_b128 v[78:81], v86 offset:1024
	ds_read_b128 v[82:85], v86 offset:2048
	ds_read_b128 v[86:89], v86 offset:3072
	ds_read_b128 v[156:159], v172
	ds_read_b128 v[164:167], v172 offset:1024
	ds_read_b128 v[168:171], v172 offset:2048
	ds_read_b128 v[172:175], v172 offset:3072
	s_add_u32 s28, s28, s10
	s_addc_u32 s29, s29, 0
	s_mov_b32 m0, s78
	ds_read_b128 v[176:179], v163 offset:32768
	ds_read_b128 v[180:183], v163 offset:33792
	ds_read_b128 v[184:187], v163 offset:34816
	ds_read_b128 v[188:191], v163 offset:35840
	ds_read_b128 v[192:195], v163 offset:36864
	ds_read_b128 v[196:199], v163 offset:37888
	ds_read_b128 v[200:203], v163 offset:38912
	ds_read_b128 v[210:213], v163 offset:39936
	global_load_lds_dwordx4 v146, s[28:29]
	s_mov_b32 m0, s79
	s_nop 0
	global_load_lds_dwordx4 v148, s[28:29]
	s_sub_u32 s28, s28, s10
	s_subb_u32 s29, s29, 0
	s_waitcnt vmcnt(8)
	s_waitcnt lgkmcnt(0)
	s_barrier
	s_setprio 1
	s_waitcnt lgkmcnt(0)
	v_mfma_f32_16x16x32_bf16 v[142:145], v[74:77], v[176:179], v[142:145]
	v_mfma_f32_16x16x32_bf16 v[138:141], v[82:85], v[176:179], v[138:141]
	v_mfma_f32_16x16x32_bf16 v[126:129], v[74:77], v[184:187], v[126:129]
	v_mfma_f32_16x16x32_bf16 v[122:125], v[82:85], v[184:187], v[122:125]
	v_mfma_f32_16x16x32_bf16 v[110:113], v[74:77], v[192:195], v[110:113]
	v_mfma_f32_16x16x32_bf16 v[106:109], v[82:85], v[192:195], v[106:109]
	v_mfma_f32_16x16x32_bf16 v[94:97], v[74:77], v[200:203], v[94:97]
	v_mfma_f32_16x16x32_bf16 v[90:93], v[82:85], v[200:203], v[90:93]
	v_mfma_f32_16x16x32_bf16 v[142:145], v[78:81], v[180:183], v[142:145]
	v_mfma_f32_16x16x32_bf16 v[138:141], v[86:89], v[180:183], v[138:141]
	v_mfma_f32_16x16x32_bf16 v[126:129], v[78:81], v[188:191], v[126:129]
	v_mfma_f32_16x16x32_bf16 v[122:125], v[86:89], v[188:191], v[122:125]
	v_mfma_f32_16x16x32_bf16 v[110:113], v[78:81], v[196:199], v[110:113]
	v_mfma_f32_16x16x32_bf16 v[106:109], v[86:89], v[196:199], v[106:109]
	v_mfma_f32_16x16x32_bf16 v[94:97], v[78:81], v[210:213], v[94:97]
	v_mfma_f32_16x16x32_bf16 v[90:93], v[86:89], v[210:213], v[90:93]
	s_setprio 0
	s_setprio 1
	v_mfma_f32_16x16x32_bf16 v[134:137], v[156:159], v[176:179], v[134:137]
	v_mfma_f32_16x16x32_bf16 v[130:133], v[168:171], v[176:179], v[130:133]
	v_mfma_f32_16x16x32_bf16 v[118:121], v[156:159], v[184:187], v[118:121]
	v_mfma_f32_16x16x32_bf16 v[114:117], v[168:171], v[184:187], v[114:117]
	v_mfma_f32_16x16x32_bf16 v[102:105], v[156:159], v[192:195], v[102:105]
	v_mfma_f32_16x16x32_bf16 v[98:101], v[168:171], v[192:195], v[98:101]
	v_mfma_f32_16x16x32_bf16 v[70:73], v[156:159], v[200:203], v[70:73]
	v_mfma_f32_16x16x32_bf16 v[66:69], v[168:171], v[200:203], v[66:69]
	v_mfma_f32_16x16x32_bf16 v[134:137], v[164:167], v[180:183], v[134:137]
	v_mfma_f32_16x16x32_bf16 v[130:133], v[172:175], v[180:183], v[130:133]
	v_mfma_f32_16x16x32_bf16 v[118:121], v[164:167], v[188:191], v[118:121]
	v_mfma_f32_16x16x32_bf16 v[114:117], v[172:175], v[188:191], v[114:117]
	v_mfma_f32_16x16x32_bf16 v[102:105], v[164:167], v[196:199], v[102:105]
	v_mfma_f32_16x16x32_bf16 v[98:101], v[172:175], v[196:199], v[98:101]
	v_mfma_f32_16x16x32_bf16 v[70:73], v[164:167], v[210:213], v[70:73]
	v_mfma_f32_16x16x32_bf16 v[66:69], v[172:175], v[210:213], v[66:69]
	s_setprio 0
	s_barrier
	s_add_i32 m0, s62, 0x17f80
	ds_read_b128 v[176:179], v163 offset:49152
	ds_read_b128 v[180:183], v163 offset:50176
	ds_read_b128 v[184:187], v163 offset:51200
	ds_read_b128 v[188:191], v163 offset:52224
	ds_read_b128 v[192:195], v163 offset:53248
	ds_read_b128 v[196:199], v163 offset:54272
	ds_read_b128 v[200:203], v163 offset:55296
	ds_read_b128 v[210:213], v163 offset:56320
	global_load_lds_dwordx4 v0, s[100:101] offset:128
	s_add_i32 m0, s62, 0x19f80
	s_nop 0
	global_load_lds_dwordx4 v150, s[100:101] offset:128
	s_add_i32 m0, s62, 0x1bf80
	s_nop 0
	global_load_lds_dwordx4 v0, s[86:87] offset:128
	s_add_i32 m0, s62, 0x1df80
	s_nop 0
	global_load_lds_dwordx4 v150, s[86:87] offset:128
	s_add_i32 m0, s80, 0xffffff80
	s_nop 0
	global_load_lds_dwordx4 v146, s[28:29] offset:128
	s_add_i32 m0, s81, 0xffffff80
	s_nop 0
	global_load_lds_dwordx4 v148, s[28:29] offset:128
	s_waitcnt vmcnt(8)
	s_waitcnt lgkmcnt(0)
	s_barrier
	s_setprio 1
	s_waitcnt lgkmcnt(0)
	v_mfma_f32_16x16x32_bf16 v[62:65], v[74:77], v[176:179], v[62:65]
	v_mfma_f32_16x16x32_bf16 v[58:61], v[82:85], v[176:179], v[58:61]
	v_mfma_f32_16x16x32_bf16 v[46:49], v[74:77], v[184:187], v[46:49]
	v_mfma_f32_16x16x32_bf16 v[42:45], v[82:85], v[184:187], v[42:45]
	v_mfma_f32_16x16x32_bf16 v[30:33], v[74:77], v[192:195], v[30:33]
	v_mfma_f32_16x16x32_bf16 v[26:29], v[82:85], v[192:195], v[26:29]
	v_mfma_f32_16x16x32_bf16 v[14:17], v[74:77], v[200:203], v[14:17]
	v_mfma_f32_16x16x32_bf16 v[10:13], v[82:85], v[200:203], v[10:13]
	v_mfma_f32_16x16x32_bf16 v[62:65], v[78:81], v[180:183], v[62:65]
	v_mfma_f32_16x16x32_bf16 v[58:61], v[86:89], v[180:183], v[58:61]
	v_mfma_f32_16x16x32_bf16 v[46:49], v[78:81], v[188:191], v[46:49]
	v_mfma_f32_16x16x32_bf16 v[42:45], v[86:89], v[188:191], v[42:45]
	v_mfma_f32_16x16x32_bf16 v[30:33], v[78:81], v[196:199], v[30:33]
	v_mfma_f32_16x16x32_bf16 v[26:29], v[86:89], v[196:199], v[26:29]
	v_mfma_f32_16x16x32_bf16 v[14:17], v[78:81], v[210:213], v[14:17]
	v_mfma_f32_16x16x32_bf16 v[10:13], v[86:89], v[210:213], v[10:13]
	s_setprio 0
	s_setprio 1
	v_mfma_f32_16x16x32_bf16 v[54:57], v[156:159], v[176:179], v[54:57]
	v_mfma_f32_16x16x32_bf16 v[50:53], v[168:171], v[176:179], v[50:53]
	v_mfma_f32_16x16x32_bf16 v[38:41], v[156:159], v[184:187], v[38:41]
	v_mfma_f32_16x16x32_bf16 v[34:37], v[168:171], v[184:187], v[34:37]
	v_mfma_f32_16x16x32_bf16 v[22:25], v[156:159], v[192:195], v[22:25]
	v_mfma_f32_16x16x32_bf16 v[18:21], v[168:171], v[192:195], v[18:21]
	v_mfma_f32_16x16x32_bf16 v[6:9], v[156:159], v[200:203], v[6:9]
	v_mfma_f32_16x16x32_bf16 v[2:5], v[168:171], v[200:203], v[2:5]
	v_mfma_f32_16x16x32_bf16 v[54:57], v[164:167], v[180:183], v[54:57]
	v_mfma_f32_16x16x32_bf16 v[50:53], v[172:175], v[180:183], v[50:53]
	v_mfma_f32_16x16x32_bf16 v[38:41], v[164:167], v[188:191], v[38:41]
	v_mfma_f32_16x16x32_bf16 v[34:37], v[172:175], v[188:191], v[34:37]
	v_mfma_f32_16x16x32_bf16 v[22:25], v[164:167], v[196:199], v[22:25]
	v_mfma_f32_16x16x32_bf16 v[18:21], v[172:175], v[196:199], v[18:21]
	v_mfma_f32_16x16x32_bf16 v[6:9], v[164:167], v[210:213], v[6:9]
	v_mfma_f32_16x16x32_bf16 v[2:5], v[172:175], v[210:213], v[2:5]
	s_setprio 0
	s_barrier
	s_add_u32 s14, s14, 0x100
	s_addc_u32 s15, s15, 0
	s_add_u32 s47, s47, 0x100
	s_addc_u32 vcc_lo, vcc_lo, 0
	s_cmp_ge_u32 vcc_hi, s82
	s_mov_b32 s28, vcc_hi
	s_cbranch_scc0 .LBB0_410
	s_and_b64 vcc, exec, s[34:35]
	s_cbranch_vccz .LBB0_413
	s_barrier
